# counted waits at the head of the GQA/MLA QK^T sections: four K reads reordered into consumption order, lgkmcnt 3/2/3/2 instead of one full drain
# baseline (speedup 1.0000x reference)
; __device__ __forceinline__ void finishSM(f32x16& p0, f32x16& p1, float alpha, float& l_reg, bf16x8& pa0, bf16x8& pa1, bf16x8& pa2, bf16x8& pa3) {
; #pragma unroll
;   for (int r = 0; r < 16; ++r) p1[r] = __builtin_amdgcn_exp2f(p1[r]);
;   float ps = 0;
; #pragma unroll
;   for (int r = 0; r < 16; ++r) ps += p0[r];
; #pragma unroll
;   for (int r = 0; r < 16; ++r) ps += p1[r];
;   { auto rr = __builtin_amdgcn_permlane32_swap(__float_as_uint(ps), __float_as_uint(ps), false, false);
;     ps = __uint_as_float(rr[0]) + __uint_as_float(rr[1]); }
;   l_reg = l_reg * alpha + ps;
;     ...
;   PK4(p0, 0, pa0); PK4(p0, 8, pa1); PK4(p1, 0, pa2); PK4(p1, 8, pa3);
; template <int DQK, int KW, int QSP> __device__ __forceinline__ void qkt(f32x16& p0, f32x16& p1, const char* Ks, const int (&kb)[4], const bf16x8* qr, const char* qsp, const f32x16& cinit) {
;   p0 = cinit; p1 = cinit;
;   constexpr int N = DQK / 16;
;     ...
;   bf16x8 f0[2], f1[2];
;   f0[0] = KRD(0, 1); f1[0] = KRD(0, 0);
; #pragma unroll
;   for (int d0 = 0; d0 < N; ++d0) {
;     if (d0 + 1 < N) { f0[(d0 + 1) & 1] = KRD(d0 + 1, 1); f1[(d0 + 1) & 1] = KRD(d0 + 1, 0); }
;     __builtin_amdgcn_sched_barrier(0x406);
;     bf16x8 qf;
;     if constexpr (QSP > 0) { if (d0 >= N - QSP) qf = *reinterpret_cast<const bf16x8*>(qsp + (d0 - (N - QSP)) * 1024); else qf = qr[d0]; } else qf = qr[d0];
;     p0 = __builtin_amdgcn_mfma_f32_32x32x16_bf16(f0[d0 & 1], qf, p0, 0, 0, 0);
;     p1 = __builtin_amdgcn_mfma_f32_32x32x16_bf16(f1[d0 & 1], qf, p1, 0, 0, 0);
;     __builtin_amdgcn_sched_barrier(0x406); }
.LBB0_51:
	s_mul_i32 s6, s8, 0x6000
	s_add_i32 s6, s6, 0
	v_add_u32_e32 v210, s6, v207
	v_add_u32_e32 v211, s6, v200
	ds_read_b128 v[70:73], v211 offset:49152
	ds_read_b128 v[66:69], v211 offset:61440
	ds_read_b128 v[158:161], v210 offset:61440
	ds_read_b128 v[154:157], v210 offset:49152
	v_add_u32_e32 v223, s6, v205
	v_add_u32_e32 v229, s6, v206
	s_waitcnt lgkmcnt(3)
	v_mfma_f32_32x32x16_bf16 v[82:97], v[70:73], v[130:133], 0
	v_exp_f32_e32 v182, v182
	v_exp_f32_e32 v183, v183
	v_exp_f32_e32 v180, v180
	v_exp_f32_e32 v181, v181
	v_exp_f32_e32 v178, v178
	v_exp_f32_e32 v179, v179
	v_exp_f32_e32 v176, v176
	s_waitcnt lgkmcnt(2)
	v_mfma_f32_32x32x16_bf16 v[66:81], v[66:69], v[130:133], 0
	ds_read_b128 v[230:233], v223 offset:49152
	ds_read_b128 v[234:237], v223 offset:61440
	v_exp_f32_e32 v177, v177
	v_exp_f32_e32 v168, v168
	v_exp_f32_e32 v169, v169
	v_exp_f32_e32 v167, v167
	s_waitcnt lgkmcnt(3)
	v_mfma_f32_32x32x16_bf16 v[66:81], v[158:161], v[126:129], v[66:81]
	s_waitcnt lgkmcnt(2)
	v_mfma_f32_32x32x16_bf16 v[82:97], v[154:157], v[126:129], v[82:97]
	ds_read_b128 v[154:157], v229 offset:49152
	ds_read_b128 v[158:161], v229 offset:61440
	s_waitcnt lgkmcnt(2)
	v_mfma_f32_32x32x16_bf16 v[66:81], v[234:237], v[122:125], v[66:81]
	v_mfma_f32_32x32x16_bf16 v[82:97], v[230:233], v[122:125], v[82:97]
	ds_read_b128 v[230:233], v211 offset:49280
	ds_read_b128 v[234:237], v211 offset:61568
	s_waitcnt lgkmcnt(2)
	v_mfma_f32_32x32x16_bf16 v[66:81], v[158:161], v[118:121], v[66:81]
	v_mfma_f32_32x32x16_bf16 v[82:97], v[154:157], v[118:121], v[82:97]
	ds_read_b128 v[154:157], v210 offset:49280
	ds_read_b128 v[158:161], v210 offset:61568
	s_waitcnt lgkmcnt(2)
	v_mfma_f32_32x32x16_bf16 v[66:81], v[234:237], v[114:117], v[66:81]
	v_mfma_f32_32x32x16_bf16 v[82:97], v[230:233], v[114:117], v[82:97]
	ds_read_b128 v[230:233], v223 offset:49280
	ds_read_b128 v[234:237], v223 offset:61568
	s_waitcnt lgkmcnt(2)
	v_mfma_f32_32x32x16_bf16 v[66:81], v[158:161], v[110:113], v[66:81]
	v_mfma_f32_32x32x16_bf16 v[82:97], v[154:157], v[110:113], v[82:97]
	ds_read_b128 v[154:157], v229 offset:49280
	ds_read_b128 v[158:161], v229 offset:61568
	s_waitcnt lgkmcnt(2)
	v_mfma_f32_32x32x16_bf16 v[66:81], v[234:237], v[106:109], v[66:81]
	v_mfma_f32_32x32x16_bf16 v[82:97], v[230:233], v[106:109], v[82:97]
	ds_read_b128 v[230:233], v211 offset:49408
	ds_read_b128 v[234:237], v211 offset:61696
	s_waitcnt lgkmcnt(2)
	v_mfma_f32_32x32x16_bf16 v[66:81], v[158:161], v[102:105], v[66:81]
	v_mfma_f32_32x32x16_bf16 v[82:97], v[154:157], v[102:105], v[82:97]
	ds_read_b128 v[154:157], v210 offset:49408
	ds_read_b128 v[158:161], v210 offset:61696
	s_waitcnt lgkmcnt(2)
	v_mfma_f32_32x32x16_bf16 v[66:81], v[234:237], v[98:101], v[66:81]
	v_mfma_f32_32x32x16_bf16 v[82:97], v[230:233], v[98:101], v[82:97]
	ds_read_b128 v[230:233], v223 offset:49408
	ds_read_b128 v[234:237], v223 offset:61696
	v_exp_f32_e32 v223, v166
	s_waitcnt lgkmcnt(2)
	v_mfma_f32_32x32x16_bf16 v[66:81], v[158:161], v[248:251], v[66:81]
	v_mfma_f32_32x32x16_bf16 v[82:97], v[154:157], v[248:251], v[82:97]
	ds_read_b128 v[158:161], v229 offset:49408
	ds_read_b128 v[154:157], v229 offset:61696
	ds_read_b128 v[238:241], v197 offset:1024
	v_exp_f32_e32 v229, v164
	s_waitcnt lgkmcnt(0)
	v_mfma_f32_32x32x16_bf16 v[66:81], v[234:237], v[238:241], v[66:81]
	v_mfma_f32_32x32x16_bf16 v[82:97], v[230:233], v[238:241], v[82:97]
	ds_read_b128 v[230:233], v197 offset:2048
	s_waitcnt lgkmcnt(0)
	v_mfma_f32_32x32x16_bf16 v[66:81], v[154:157], v[230:233], v[66:81]
	v_add_f32_e32 v154, 0, v226
	v_add_f32_e32 v154, v228, v154
	v_add_f32_e32 v154, v224, v154
	v_add_f32_e32 v154, v227, v154
	v_add_f32_e32 v154, v221, v154
	v_add_f32_e32 v154, v225, v154
	v_add_f32_e32 v154, v220, v154
	v_add_f32_e32 v154, v222, v154
	v_add_f32_e32 v154, v217, v154
	v_add_f32_e32 v154, v219, v154
	v_add_f32_e32 v154, v215, v154
	v_add_f32_e32 v154, v218, v154
	v_add_f32_e32 v154, v213, v154
	v_add_f32_e32 v154, v216, v154
	v_add_f32_e32 v154, v212, v154
	v_add_f32_e32 v154, v214, v154
	v_add_f32_e32 v154, v182, v154
	v_add_f32_e32 v154, v183, v154
	v_add_f32_e32 v154, v180, v154
	v_add_f32_e32 v154, v181, v154
	v_add_f32_e32 v154, v178, v154
	v_add_f32_e32 v154, v179, v154
	v_add_f32_e32 v154, v176, v154
	v_add_f32_e32 v154, v177, v154
	v_add_f32_e32 v154, v168, v154
	v_mfma_f32_32x32x16_bf16 v[82:97], v[158:161], v[230:233], v[82:97]
	v_exp_f32_e32 v230, v165
	v_add_f32_e32 v154, v169, v154
	v_exp_f32_e32 v231, v162
	v_add_f32_e32 v154, v223, v154
	v_exp_f32_e32 v232, v163
	v_add_f32_e32 v154, v167, v154
	v_add_f32_e32 v154, v229, v154
	v_add_f32_e32 v154, v230, v154
	v_add_f32_e32 v154, v231, v154
	v_add_f32_e32 v210, v232, v154
	v_mov_b32_e32 v211, v210
	v_cvt_pk_bf16_f32 v154, v226, v228
	v_cvt_pk_bf16_f32 v155, v224, v227
	v_cvt_pk_bf16_f32 v156, v221, v225
	s_nop 1
	v_permlane32_swap_b32_e32 v210, v211
	v_cvt_pk_bf16_f32 v157, v220, v222
	v_permlane32_swap_b32_e32 v154, v156
	v_cvt_pk_bf16_f32 v158, v217, v219
	v_cvt_pk_bf16_f32 v159, v215, v218
	v_cvt_pk_bf16_f32 v160, v213, v216
	v_cvt_pk_bf16_f32 v161, v212, v214
	v_cvt_pk_bf16_f32 v162, v182, v183
	v_cvt_pk_bf16_f32 v163, v180, v181
	v_cvt_pk_bf16_f32 v164, v178, v179
	v_cvt_pk_bf16_f32 v165, v176, v177
	v_cvt_pk_bf16_f32 v166, v168, v169
	v_cvt_pk_bf16_f32 v167, v223, v167
	v_cvt_pk_bf16_f32 v168, v229, v230
	v_cvt_pk_bf16_f32 v169, v231, v232
	v_permlane32_swap_b32_e32 v155, v157
	v_permlane32_swap_b32_e32 v158, v160
	v_permlane32_swap_b32_e32 v159, v161
	v_permlane32_swap_b32_e32 v162, v164
	v_permlane32_swap_b32_e32 v163, v165
	v_permlane32_swap_b32_e32 v166, v168
	v_permlane32_swap_b32_e32 v167, v169
	s_lshl_b32 s10, s2, 14
	s_add_i32 s9, s10, 0
	v_add_u32_e32 v176, s9, v201
	s_lshl_b32 s6, s2, 13
	s_waitcnt vmcnt(0)
; #define SBAR() __builtin_amdgcn_sched_barrier(0)
; template <int DQK> __device__ __forceinline__ void partialSM(f32x16& p0, f32x16& p1, float& m_reg, float& mn, float& alpha) {
;   constexpr float SCALE = Sc<DQK>::SCALE; constexpr float C = SCALE * 1.4426950408889634f;
;   float pmax = p0[0];
; #pragma unroll
;   for (int r = 1; r < 16; ++r) pmax = fmaxf(pmax, p0[r]);
; #pragma unroll
;   for (int r = 0; r < 16; ++r) pmax = fmaxf(pmax, p1[r]);
;   { auto rr = __builtin_amdgcn_permlane32_swap(__float_as_uint(pmax), __float_as_uint(pmax), false, false);
;     pmax = fmaxf(__uint_as_float(rr[0]), __uint_as_float(rr[1])); }
;   if (__builtin_expect(__all(pmax - m_reg <= THR / SCALE), 1)) { mn = m_reg; alpha = 1.f; }
;   else { mn = fmaxf(m_reg, pmax); alpha = __builtin_amdgcn_exp2f((m_reg - mn) * C); m_reg = mn; }
; template <int D0> __device__ __forceinline__ void pv_one(f32x16& od, int vb, bf16x8 pa0, bf16x8 pa1, bf16x8 pa2, bf16x8 pa3) {
;   const s16x4 l0 = tr_read<v_rd_off(D0, 0, 0)>(vb), h0 = tr_read<v_rd_off(D0, 0, 1)>(vb), l1 = tr_read<v_rd_off(D0, 1, 0)>(vb), h1 = tr_read<v_rd_off(D0, 1, 1)>(vb);
;   const s16x4 l2 = tr_read<v_rd_off(D0, 2, 0)>(vb), h2 = tr_read<v_rd_off(D0, 2, 1)>(vb), l3 = tr_read<v_rd_off(D0, 3, 0)>(vb), h3 = tr_read<v_rd_off(D0, 3, 1)>(vb);
;   asm volatile("s_waitcnt lgkmcnt(0)" ::: "memory"); SBAR();
;     ...
;   od = __builtin_amdgcn_mfma_f32_32x32x16_bf16(pa0, PK(l0, h0), od, 0, 0, 0);
;   od = __builtin_amdgcn_mfma_f32_32x32x16_bf16(pa1, PK(l1, h1), od, 0, 0, 0);
;   od = __builtin_amdgcn_mfma_f32_32x32x16_bf16(pa2, PK(l2, h2), od, 0, 0, 0);
;   od = __builtin_amdgcn_mfma_f32_32x32x16_bf16(pa3, PK(l3, h3), od, 0, 0, 0);
;     ...
; }
	s_waitcnt vmcnt(4)
	ds_write_b128 v176, v[134:137]
	v_add_u32_e32 v134, s9, v202
	s_add_i32 s9, s9, s6
	s_waitcnt vmcnt(3)
	ds_write_b128 v134, v[138:141]
	v_add_u32_e32 v134, s9, v203
	s_waitcnt vmcnt(2)
	ds_write_b128 v134, v[142:145] offset:49152
	s_waitcnt vmcnt(1)
	ds_write_b128 v134, v[146:149] offset:61440
	v_add_u32_e32 v134, s9, v204
	v_lshl_add_u64 v[176:177], s[94:95], 0, v[174:175]
	s_mov_b32 s6, 0x198c0000
	s_waitcnt vmcnt(0)
	ds_write_b128 v134, v[150:153] offset:49152
	v_add_co_u32_e32 v134, vcc, s6, v176
	s_mov_b32 s6, 0x198e0000
	s_nop 0
	v_addc_co_u32_e32 v135, vcc, 0, v177, vcc
	v_add_co_u32_e32 v138, vcc, s6, v176
	s_mov_b32 s6, 0x150c0000
	s_nop 0
	v_addc_co_u32_e32 v139, vcc, 0, v177, vcc
	v_add_co_u32_e32 v142, vcc, s6, v176
	s_mov_b32 s6, 0x150e0000
	s_nop 0
	v_addc_co_u32_e32 v143, vcc, 0, v177, vcc
	v_add_co_u32_e32 v146, vcc, s6, v176
	v_lshl_add_u64 v[178:179], s[94:95], 0, v[172:173]
	s_nop 0
	v_addc_co_u32_e32 v147, vcc, 0, v177, vcc
	s_mov_b32 s6, 0x9906000
	v_add_co_u32_e32 v150, vcc, s6, v178
	global_load_dwordx4 v[134:137], v[134:135], off
	s_nop 0
	global_load_dwordx4 v[138:141], v[138:139], off
	v_addc_co_u32_e32 v151, vcc, 0, v179, vcc
	global_load_dwordx4 v[142:145], v[142:143], off
	s_nop 0
	global_load_dwordx4 v[146:149], v[146:147], off
	s_nop 0
	global_load_dwordx4 v[150:153], v[150:151], off
	v_lshl_add_u32 v224, s48, 14, v196
	ds_read_b64_tr_b16 v[180:181], v224 offset:0
	ds_read_b64_tr_b16 v[182:183], v224 offset:0x800
	ds_read_b64_tr_b16 v[212:213], v224 offset:0x1000
	ds_read_b64_tr_b16 v[214:215], v224 offset:0x1800
	ds_read_b64_tr_b16 v[216:217], v224 offset:0x2000
	ds_read_b64_tr_b16 v[218:219], v224 offset:0x2800
	ds_read_b64_tr_b16 v[220:221], v224 offset:0x3000
	ds_read_b64_tr_b16 v[222:223], v224 offset:0x3800
	s_waitcnt lgkmcnt(6)
	s_nop 0
	v_mfma_f32_32x32x16_bf16 v[2:17], v[154:157], v[180:183], v[2:17]
	ds_read_b64_tr_b16 v[180:181], v224 offset:0x200
	ds_read_b64_tr_b16 v[182:183], v224 offset:0xa00
	s_waitcnt lgkmcnt(6)
	v_mfma_f32_32x32x16_bf16 v[2:17], v[158:161], v[212:215], v[2:17]
	ds_read_b64_tr_b16 v[212:213], v224 offset:0x1200
	ds_read_b64_tr_b16 v[214:215], v224 offset:0x1a00
	s_waitcnt lgkmcnt(6)
	v_mfma_f32_32x32x16_bf16 v[2:17], v[162:165], v[216:219], v[2:17]
	ds_read_b64_tr_b16 v[216:217], v224 offset:0x2200
	ds_read_b64_tr_b16 v[218:219], v224 offset:0x2a00
	s_waitcnt lgkmcnt(6)
	v_mfma_f32_32x32x16_bf16 v[2:17], v[166:169], v[220:223], v[2:17]
	ds_read_b64_tr_b16 v[220:221], v224 offset:0x3200
	ds_read_b64_tr_b16 v[222:223], v224 offset:0x3a00
	s_waitcnt lgkmcnt(6)
	v_mfma_f32_32x32x16_bf16 v[50:65], v[154:157], v[180:183], v[50:65]
	ds_read_b64_tr_b16 v[180:181], v224 offset:0x400
	ds_read_b64_tr_b16 v[182:183], v224 offset:0xc00
	s_waitcnt lgkmcnt(6)
	v_mfma_f32_32x32x16_bf16 v[50:65], v[158:161], v[212:215], v[50:65]
	ds_read_b64_tr_b16 v[212:213], v224 offset:0x1400
	ds_read_b64_tr_b16 v[214:215], v224 offset:0x1c00
	s_waitcnt lgkmcnt(6)
	v_mfma_f32_32x32x16_bf16 v[50:65], v[162:165], v[216:219], v[50:65]
	ds_read_b64_tr_b16 v[216:217], v224 offset:0x2400
	ds_read_b64_tr_b16 v[218:219], v224 offset:0x2c00
	s_waitcnt lgkmcnt(6)
	v_mfma_f32_32x32x16_bf16 v[50:65], v[166:169], v[220:223], v[50:65]
	ds_read_b64_tr_b16 v[220:221], v224 offset:0x3400
	ds_read_b64_tr_b16 v[222:223], v224 offset:0x3c00
	s_waitcnt lgkmcnt(6)
	v_mfma_f32_32x32x16_bf16 v[34:49], v[154:157], v[180:183], v[34:49]
	ds_read_b64_tr_b16 v[180:181], v224 offset:0x600
	ds_read_b64_tr_b16 v[182:183], v224 offset:0xe00
	s_waitcnt lgkmcnt(6)
	v_mfma_f32_32x32x16_bf16 v[34:49], v[158:161], v[212:215], v[34:49]
	ds_read_b64_tr_b16 v[212:213], v224 offset:0x1600
	ds_read_b64_tr_b16 v[214:215], v224 offset:0x1e00
	s_waitcnt lgkmcnt(6)
	v_mfma_f32_32x32x16_bf16 v[34:49], v[162:165], v[216:219], v[34:49]
	ds_read_b64_tr_b16 v[216:217], v224 offset:0x2600
	ds_read_b64_tr_b16 v[218:219], v224 offset:0x2e00
	s_waitcnt lgkmcnt(6)
	v_mfma_f32_32x32x16_bf16 v[34:49], v[166:169], v[220:223], v[34:49]
	ds_read_b64_tr_b16 v[220:221], v224 offset:0x3600
	ds_read_b64_tr_b16 v[222:223], v224 offset:0x3e00
	s_waitcnt lgkmcnt(6)
	v_mfma_f32_32x32x16_bf16 v[18:33], v[154:157], v[180:183], v[18:33]
	v_max_f32_e32 v154, v83, v83
	v_max_f32_e32 v155, v82, v82
	v_max_f32_e32 v154, v155, v154
	v_max3_f32 v154, v154, v84, v85
	v_max3_f32 v154, v154, v86, v87
	v_max3_f32 v154, v154, v88, v89
	v_max3_f32 v154, v154, v90, v91
	v_max3_f32 v154, v154, v92, v93
	v_max3_f32 v154, v154, v94, v95
	s_waitcnt lgkmcnt(4)
	v_mfma_f32_32x32x16_bf16 v[18:33], v[158:161], v[212:215], v[18:33]
	v_max3_f32 v154, v154, v96, v97
	v_max3_f32 v154, v154, v66, v67
	v_max3_f32 v154, v154, v68, v69
	v_max3_f32 v154, v154, v70, v71
	v_max3_f32 v154, v154, v72, v73
	v_max3_f32 v154, v154, v74, v75
	v_max3_f32 v154, v154, v76, v77
	v_max3_f32 v154, v154, v78, v79
	s_waitcnt lgkmcnt(2)
	v_mfma_f32_32x32x16_bf16 v[18:33], v[162:165], v[216:219], v[18:33]
	v_max3_f32 v154, v154, v80, v81
	v_mov_b32_e32 v155, v154
	s_nop 1
	v_permlane32_swap_b32_e32 v154, v155
	v_max_f32_e32 v155, v155, v155
	v_max_f32_e32 v154, v154, v154
	v_max_f32_e32 v154, v154, v155
	v_sub_f32_e32 v155, v154, v209
	v_cmp_ge_f32_e32 vcc, s49, v155
	v_max_f32_e32 v155, v209, v209
	v_max_f32_e32 v154, v155, v154
	s_waitcnt lgkmcnt(0)
	v_mfma_f32_32x32x16_bf16 v[18:33], v[166:169], v[220:223], v[18:33]
	v_sub_f32_e32 v155, v209, v154
	v_mul_f32_e32 v155, 0x3dd53b94, v155
	v_exp_f32_e32 v155, v155
	s_cmp_eq_u64 vcc, exec
	s_cselect_b64 s[40:41], -1, 0
	s_waitcnt lgkmcnt(0)
	s_barrier
	v_cndmask_b32_e64 v223, v155, 1.0, s[40:41]
	v_cmp_gt_f32_e32 vcc, 1.0, v223
	s_cbranch_vccz .LBB0_55
; template <int DQK> __device__ __forceinline__ void partialSM(f32x16& p0, f32x16& p1, float& m_reg, float& mn, float& alpha) {
;     ...
;   float mnC = -mn * C;
; #pragma unroll
;   for (int r = 0; r < 16; ++r) p0[r] = fmaf(p0[r], C, mnC);
; #pragma unroll
;   for (int r = 0; r < 16; ++r) p1[r] = fmaf(p1[r], C, mnC);
; #pragma unroll
;   for (int r = 0; r < 16; ++r) p0[r] = __builtin_amdgcn_exp2f(p0[r]);
; template <int DQK, int KW, int QSP> __device__ __forceinline__ void qkt(f32x16& p0, f32x16& p1, const char* Ks, const int (&kb)[4], const bf16x8* qr, const char* qsp, const f32x16& cinit) {
;   p0 = cinit; p1 = cinit;
;   constexpr int N = DQK / 16;
;     ...
;   bf16x8 f0[2], f1[2];
;   f0[0] = KRD(0, 1); f1[0] = KRD(0, 0);
; #pragma unroll
;   for (int d0 = 0; d0 < N; ++d0) {
;     if (d0 + 1 < N) { f0[(d0 + 1) & 1] = KRD(d0 + 1, 1); f1[(d0 + 1) & 1] = KRD(d0 + 1, 0); }
;     __builtin_amdgcn_sched_barrier(0x406);
;     bf16x8 qf;
;     if constexpr (QSP > 0) { if (d0 >= N - QSP) qf = *reinterpret_cast<const bf16x8*>(qsp + (d0 - (N - QSP)) * 1024); else qf = qr[d0]; } else qf = qr[d0];
;     p0 = __builtin_amdgcn_mfma_f32_32x32x16_bf16(f0[d0 & 1], qf, p0, 0, 0, 0);
;     p1 = __builtin_amdgcn_mfma_f32_32x32x16_bf16(f1[d0 & 1], qf, p1, 0, 0, 0);
;     __builtin_amdgcn_sched_barrier(0x406); }
	s_and_saveexec_b64 s[6:7], s[38:39]
	ds_write_b32 v198, v223 offset:128
	s_or_b64 exec, exec, s[6:7]
	s_waitcnt lgkmcnt(0)
	v_add_u32_e32 v155, v195, v170
	ds_read_b128 v[156:159], v155 offset:224
	ds_read_b128 v[160:163], v155 offset:192
	ds_read_b128 v[164:167], v155 offset:160
	ds_read_b128 v[180:183], v155 offset:128
	s_waitcnt lgkmcnt(3)
	v_pk_mul_f32 v[14:15], v[14:15], v[156:157]
	s_waitcnt lgkmcnt(2)
	v_pk_mul_f32 v[10:11], v[10:11], v[160:161]
	s_waitcnt lgkmcnt(1)
	v_pk_mul_f32 v[6:7], v[6:7], v[164:165]
	v_pk_mul_f32 v[16:17], v[16:17], v[158:159]
	v_pk_mul_f32 v[12:13], v[12:13], v[162:163]
	v_pk_mul_f32 v[8:9], v[8:9], v[166:167]
	s_waitcnt lgkmcnt(0)
	v_pk_mul_f32 v[4:5], v[4:5], v[182:183]
	v_pk_mul_f32 v[2:3], v[2:3], v[180:181]
	v_pk_mul_f32 v[62:63], v[62:63], v[156:157]
	v_pk_mul_f32 v[58:59], v[58:59], v[160:161]
	v_pk_mul_f32 v[54:55], v[54:55], v[164:165]
	v_pk_mul_f32 v[64:65], v[64:65], v[158:159]
	v_pk_mul_f32 v[60:61], v[60:61], v[162:163]
	v_pk_mul_f32 v[56:57], v[56:57], v[166:167]
	v_pk_mul_f32 v[52:53], v[52:53], v[182:183]
	v_pk_mul_f32 v[50:51], v[50:51], v[180:181]
	v_pk_mul_f32 v[46:47], v[46:47], v[156:157]
	v_pk_mul_f32 v[42:43], v[42:43], v[160:161]
	v_pk_mul_f32 v[38:39], v[38:39], v[164:165]
	v_pk_mul_f32 v[48:49], v[48:49], v[158:159]
	v_pk_mul_f32 v[44:45], v[44:45], v[162:163]
	v_pk_mul_f32 v[40:41], v[40:41], v[166:167]
	v_pk_mul_f32 v[36:37], v[36:37], v[182:183]
	v_pk_mul_f32 v[34:35], v[34:35], v[180:181]
	v_pk_mul_f32 v[30:31], v[30:31], v[156:157]
	v_pk_mul_f32 v[26:27], v[26:27], v[160:161]
	v_pk_mul_f32 v[22:23], v[22:23], v[164:165]
	v_pk_mul_f32 v[32:33], v[32:33], v[158:159]
	v_pk_mul_f32 v[28:29], v[28:29], v[162:163]
	v_pk_mul_f32 v[24:25], v[24:25], v[166:167]
	v_pk_mul_f32 v[20:21], v[20:21], v[182:183]
	v_pk_mul_f32 v[18:19], v[18:19], v[180:181]
.LBB0_55:
	v_cndmask_b32_e64 v180, v154, v209, s[40:41]
	v_mul_f32_e32 v213, 0xbdd53b94, v180
	v_fmamk_f32 v82, v82, 0x3dd53b94, v213
	v_fmamk_f32 v83, v83, 0x3dd53b94, v213
	v_fmamk_f32 v84, v84, 0x3dd53b94, v213
	v_fmamk_f32 v90, v90, 0x3dd53b94, v213
	v_fmamk_f32 v91, v91, 0x3dd53b94, v213
	v_fmamk_f32 v92, v92, 0x3dd53b94, v213
	v_fmamk_f32 v93, v93, 0x3dd53b94, v213
	v_fmamk_f32 v94, v94, 0x3dd53b94, v213
	v_exp_f32_e32 v165, v82
	v_exp_f32_e32 v168, v83
	v_exp_f32_e32 v169, v84
	v_exp_f32_e32 v162, v90
	v_exp_f32_e32 v163, v91
	v_exp_f32_e32 v164, v92
	v_exp_f32_e32 v166, v93
	v_exp_f32_e32 v167, v94
	s_add_i32 s6, s2, 1
	s_cmp_lg_u32 s2, 2
	v_fmamk_f32 v85, v85, 0x3dd53b94, v213
	v_fmamk_f32 v86, v86, 0x3dd53b94, v213
	v_fmamk_f32 v87, v87, 0x3dd53b94, v213
	v_fmamk_f32 v88, v88, 0x3dd53b94, v213
	v_fmamk_f32 v89, v89, 0x3dd53b94, v213
	v_fmamk_f32 v95, v95, 0x3dd53b94, v213
	v_fmamk_f32 v96, v96, 0x3dd53b94, v213
	v_fmamk_f32 v97, v97, 0x3dd53b94, v213
	v_fmamk_f32 v229, v77, 0x3dd53b94, v213
	v_fmamk_f32 v230, v78, 0x3dd53b94, v213
	s_cselect_b32 s12, s6, 0
	v_fmamk_f32 v217, v66, 0x3dd53b94, v213
	v_fmamk_f32 v218, v67, 0x3dd53b94, v213
	v_fmamk_f32 v219, v68, 0x3dd53b94, v213
	v_fmamk_f32 v220, v69, 0x3dd53b94, v213
	v_fmamk_f32 v221, v70, 0x3dd53b94, v213
	v_fmamk_f32 v222, v71, 0x3dd53b94, v213
	v_fmamk_f32 v224, v72, 0x3dd53b94, v213
	v_fmamk_f32 v225, v73, 0x3dd53b94, v213
	v_fmamk_f32 v226, v74, 0x3dd53b94, v213
	v_fmamk_f32 v227, v75, 0x3dd53b94, v213
	v_fmamk_f32 v228, v76, 0x3dd53b94, v213
	v_fmamk_f32 v231, v79, 0x3dd53b94, v213
	v_fmamk_f32 v232, v80, 0x3dd53b94, v213
	v_fmac_f32_e32 v213, 0x3dd53b94, v81
	v_exp_f32_e32 v183, v85
	v_exp_f32_e32 v209, v86
	v_exp_f32_e32 v214, v87
	v_exp_f32_e32 v215, v88
	v_exp_f32_e32 v216, v89
	v_exp_f32_e32 v181, v95
	v_exp_f32_e32 v182, v96
	v_exp_f32_e32 v212, v97
	v_add_u32_e32 v233, s9, v207
	v_add_u32_e32 v242, s9, v200
	ds_read_b128 v[70:73], v242 offset:49152
	ds_read_b128 v[66:69], v242 offset:61440
	ds_read_b128 v[158:161], v233 offset:61440
	ds_read_b128 v[154:157], v233 offset:49152
	v_add_u32_e32 v243, s9, v205
	v_add_u32_e32 v246, s9, v206
	s_waitcnt lgkmcnt(3)
	v_mfma_f32_32x32x16_bf16 v[82:97], v[70:73], v[130:133], 0
	v_exp_f32_e32 v217, v217
	v_exp_f32_e32 v218, v218
	v_exp_f32_e32 v219, v219
	v_exp_f32_e32 v220, v220
	v_exp_f32_e32 v221, v221
	v_exp_f32_e32 v222, v222
	v_exp_f32_e32 v224, v224
	s_waitcnt lgkmcnt(2)
	v_mfma_f32_32x32x16_bf16 v[66:81], v[66:69], v[130:133], 0
	ds_read_b128 v[234:237], v243 offset:49152
	ds_read_b128 v[238:241], v243 offset:61440
	v_exp_f32_e32 v225, v225
	v_exp_f32_e32 v226, v226
	v_exp_f32_e32 v227, v227
	v_exp_f32_e32 v228, v228
	v_exp_f32_e32 v231, v231
	v_exp_f32_e32 v232, v232
	s_waitcnt lgkmcnt(3)
	v_mfma_f32_32x32x16_bf16 v[66:81], v[158:161], v[126:129], v[66:81]
	v_exp_f32_e32 v213, v213
	s_waitcnt lgkmcnt(2)
	v_mfma_f32_32x32x16_bf16 v[82:97], v[154:157], v[126:129], v[82:97]
	ds_read_b128 v[154:157], v246 offset:49152
	ds_read_b128 v[158:161], v246 offset:61440
	s_waitcnt lgkmcnt(2)
	v_mfma_f32_32x32x16_bf16 v[66:81], v[238:241], v[122:125], v[66:81]
	v_mfma_f32_32x32x16_bf16 v[82:97], v[234:237], v[122:125], v[82:97]
	ds_read_b128 v[234:237], v242 offset:49280
	ds_read_b128 v[238:241], v242 offset:61568
	s_waitcnt lgkmcnt(2)
	v_mfma_f32_32x32x16_bf16 v[66:81], v[158:161], v[118:121], v[66:81]
	v_mfma_f32_32x32x16_bf16 v[82:97], v[154:157], v[118:121], v[82:97]
	ds_read_b128 v[154:157], v233 offset:49280
	ds_read_b128 v[158:161], v233 offset:61568
	s_waitcnt lgkmcnt(2)
; __device__ __forceinline__ void finishSM(f32x16& p0, f32x16& p1, float alpha, float& l_reg, bf16x8& pa0, bf16x8& pa1, bf16x8& pa2, bf16x8& pa3) {
; #pragma unroll
;   for (int r = 0; r < 16; ++r) p1[r] = __builtin_amdgcn_exp2f(p1[r]);
;   float ps = 0;
; #pragma unroll
;   for (int r = 0; r < 16; ++r) ps += p0[r];
; #pragma unroll
;   for (int r = 0; r < 16; ++r) ps += p1[r];
;   { auto rr = __builtin_amdgcn_permlane32_swap(__float_as_uint(ps), __float_as_uint(ps), false, false);
;     ps = __uint_as_float(rr[0]) + __uint_as_float(rr[1]); }
;   l_reg = l_reg * alpha + ps;
;     ...
;   PK4(p0, 0, pa0); PK4(p0, 8, pa1); PK4(p1, 0, pa2); PK4(p1, 8, pa3);
;     ...
; }
; template <int DQK, int KW, int QSP> __device__ __forceinline__ void qkt(f32x16& p0, f32x16& p1, const char* Ks, const int (&kb)[4], const bf16x8* qr, const char* qsp, const f32x16& cinit) {
;   p0 = cinit; p1 = cinit;
;   constexpr int N = DQK / 16;
;     ...
;   bf16x8 f0[2], f1[2];
;   f0[0] = KRD(0, 1); f1[0] = KRD(0, 0);
; #pragma unroll
;   for (int d0 = 0; d0 < N; ++d0) {
;     if (d0 + 1 < N) { f0[(d0 + 1) & 1] = KRD(d0 + 1, 1); f1[(d0 + 1) & 1] = KRD(d0 + 1, 0); }
;     __builtin_amdgcn_sched_barrier(0x406);
;     bf16x8 qf;
;     if constexpr (QSP > 0) { if (d0 >= N - QSP) qf = *reinterpret_cast<const bf16x8*>(qsp + (d0 - (N - QSP)) * 1024); else qf = qr[d0]; } else qf = qr[d0];
;     p0 = __builtin_amdgcn_mfma_f32_32x32x16_bf16(f0[d0 & 1], qf, p0, 0, 0, 0);
;     p1 = __builtin_amdgcn_mfma_f32_32x32x16_bf16(f1[d0 & 1], qf, p1, 0, 0, 0);
;     __builtin_amdgcn_sched_barrier(0x406); }
	v_mfma_f32_32x32x16_bf16 v[66:81], v[238:241], v[114:117], v[66:81]
	v_mfma_f32_32x32x16_bf16 v[82:97], v[234:237], v[114:117], v[82:97]
	ds_read_b128 v[234:237], v243 offset:49280
	ds_read_b128 v[238:241], v243 offset:61568
	s_waitcnt lgkmcnt(2)
	v_mfma_f32_32x32x16_bf16 v[66:81], v[158:161], v[110:113], v[66:81]
	v_mfma_f32_32x32x16_bf16 v[82:97], v[154:157], v[110:113], v[82:97]
	ds_read_b128 v[154:157], v246 offset:49280
	ds_read_b128 v[158:161], v246 offset:61568
	s_waitcnt lgkmcnt(2)
	v_mfma_f32_32x32x16_bf16 v[66:81], v[238:241], v[106:109], v[66:81]
	v_mfma_f32_32x32x16_bf16 v[82:97], v[234:237], v[106:109], v[82:97]
	ds_read_b128 v[234:237], v242 offset:49408
	ds_read_b128 v[238:241], v242 offset:61696
	s_waitcnt lgkmcnt(2)
	v_mfma_f32_32x32x16_bf16 v[66:81], v[158:161], v[102:105], v[66:81]
	v_mfma_f32_32x32x16_bf16 v[82:97], v[154:157], v[102:105], v[82:97]
	ds_read_b128 v[154:157], v233 offset:49408
	ds_read_b128 v[158:161], v233 offset:61696
	v_exp_f32_e32 v233, v229
	s_waitcnt lgkmcnt(2)
	v_mfma_f32_32x32x16_bf16 v[66:81], v[238:241], v[98:101], v[66:81]
	v_mfma_f32_32x32x16_bf16 v[82:97], v[234:237], v[98:101], v[82:97]
	ds_read_b128 v[234:237], v243 offset:49408
	ds_read_b128 v[238:241], v243 offset:61696
	s_waitcnt lgkmcnt(2)
	v_mfma_f32_32x32x16_bf16 v[66:81], v[158:161], v[248:251], v[66:81]
	v_mfma_f32_32x32x16_bf16 v[82:97], v[154:157], v[248:251], v[82:97]
	ds_read_b128 v[158:161], v246 offset:49408
	ds_read_b128 v[154:157], v246 offset:61696
	ds_read_b128 v[242:245], v197 offset:1024
	s_waitcnt lgkmcnt(0)
	v_mfma_f32_32x32x16_bf16 v[66:81], v[238:241], v[242:245], v[66:81]
	v_mfma_f32_32x32x16_bf16 v[82:97], v[234:237], v[242:245], v[82:97]
	ds_read_b128 v[234:237], v197 offset:2048
	s_waitcnt lgkmcnt(0)
	v_mfma_f32_32x32x16_bf16 v[66:81], v[154:157], v[234:237], v[66:81]
	v_add_f32_e32 v154, 0, v165
	v_add_f32_e32 v154, v168, v154
	v_add_f32_e32 v154, v169, v154
	v_add_f32_e32 v154, v183, v154
	v_add_f32_e32 v154, v209, v154
	v_add_f32_e32 v154, v214, v154
	v_add_f32_e32 v154, v215, v154
	v_add_f32_e32 v154, v216, v154
	v_add_f32_e32 v154, v162, v154
	v_add_f32_e32 v154, v163, v154
	v_add_f32_e32 v154, v164, v154
	v_add_f32_e32 v154, v166, v154
	v_add_f32_e32 v154, v167, v154
	v_add_f32_e32 v154, v181, v154
	v_add_f32_e32 v154, v182, v154
	v_add_f32_e32 v154, v212, v154
	v_add_f32_e32 v154, v217, v154
	v_add_f32_e32 v154, v218, v154
	v_add_f32_e32 v154, v219, v154
	v_add_f32_e32 v154, v220, v154
	v_add_f32_e32 v154, v221, v154
	v_add_f32_e32 v154, v222, v154
	v_add_f32_e32 v154, v224, v154
	v_add_f32_e32 v154, v225, v154
	v_mfma_f32_32x32x16_bf16 v[82:97], v[158:161], v[234:237], v[82:97]
	v_exp_f32_e32 v234, v230
	v_add_f32_e32 v154, v226, v154
	v_add_f32_e32 v154, v227, v154
	v_add_f32_e32 v154, v228, v154
	v_add_f32_e32 v154, v233, v154
	v_add_f32_e32 v154, v234, v154
	v_add_f32_e32 v154, v231, v154
	v_add_f32_e32 v154, v232, v154
	v_add_f32_e32 v229, v213, v154
	v_mov_b32_e32 v230, v229
	v_cvt_pk_bf16_f32 v154, v165, v168
	v_cvt_pk_bf16_f32 v155, v169, v183
	v_cvt_pk_bf16_f32 v156, v209, v214
	v_cvt_pk_bf16_f32 v157, v215, v216
	v_cvt_pk_bf16_f32 v158, v162, v163
	v_cvt_pk_bf16_f32 v159, v164, v166
	v_cvt_pk_bf16_f32 v160, v167, v181
	v_cvt_pk_bf16_f32 v161, v182, v212
	v_cvt_pk_bf16_f32 v162, v217, v218
	v_cvt_pk_bf16_f32 v163, v219, v220
	v_cvt_pk_bf16_f32 v164, v221, v222
	v_cvt_pk_bf16_f32 v165, v224, v225
	v_cvt_pk_bf16_f32 v166, v226, v227
	v_cvt_pk_bf16_f32 v167, v228, v233
	v_cvt_pk_bf16_f32 v168, v234, v231
	v_cvt_pk_bf16_f32 v169, v232, v213
	s_nop 1
	v_permlane32_swap_b32_e32 v229, v230
	v_permlane32_swap_b32_e32 v154, v156
	v_permlane32_swap_b32_e32 v155, v157
	v_permlane32_swap_b32_e32 v158, v160
	v_permlane32_swap_b32_e32 v159, v161
	v_permlane32_swap_b32_e32 v162, v164
	v_permlane32_swap_b32_e32 v163, v165
	v_permlane32_swap_b32_e32 v166, v168
	v_permlane32_swap_b32_e32 v167, v169
	s_lshl_b32 s11, s12, 14
	s_add_i32 s13, s11, 0
	v_add_u32_e32 v181, s13, v201
	s_lshl_b32 s6, s12, 13
	s_waitcnt vmcnt(0)
	s_waitcnt vmcnt(4)
	ds_write_b128 v181, v[134:137]
	v_add_u32_e32 v181, s13, v202
	s_add_i32 s13, s13, s6
	s_cmp_ge_u32 s31, s33
	s_waitcnt vmcnt(3)
	ds_write_b128 v181, v[138:141]
	v_add_u32_e32 v181, s13, v203
	s_cselect_b64 s[6:7], -1, 0
	s_waitcnt vmcnt(2)
	ds_write_b128 v181, v[142:145] offset:49152
	s_waitcnt vmcnt(1)
	ds_write_b128 v181, v[146:149] offset:61440
	v_add_u32_e32 v181, s13, v204
	s_and_b64 vcc, exec, s[6:7]
	s_waitcnt vmcnt(0)
	ds_write_b128 v181, v[150:153] offset:49152
	s_cbranch_vccnz .LBB0_57
	v_add_co_u32_e32 v134, vcc, 0x19900000, v176
	s_nop 1
	v_addc_co_u32_e32 v135, vcc, 0, v177, vcc
	v_add_co_u32_e32 v138, vcc, 0x19920000, v176
	s_nop 1
	v_addc_co_u32_e32 v139, vcc, 0, v177, vcc
	v_add_co_u32_e32 v142, vcc, 0x15100000, v176
	global_load_dwordx4 v[134:137], v[134:135], off
	s_nop 0
	global_load_dwordx4 v[138:141], v[138:139], off
	v_addc_co_u32_e32 v143, vcc, 0, v177, vcc
	v_add_co_u32_e32 v146, vcc, 0x15120000, v176
	s_nop 1
	v_addc_co_u32_e32 v147, vcc, 0, v177, vcc
	v_add_co_u32_e32 v150, vcc, 0x9908000, v178
	global_load_dwordx4 v[142:145], v[142:143], off
	s_nop 0
	global_load_dwordx4 v[146:149], v[146:147], off
	v_addc_co_u32_e32 v151, vcc, 0, v179, vcc
	global_load_dwordx4 v[150:153], v[150:151], off

; __device__ __forceinline__ void finishSM(f32x16& p0, f32x16& p1, float alpha, float& l_reg, bf16x8& pa0, bf16x8& pa1, bf16x8& pa2, bf16x8& pa3) {
; #pragma unroll
;   for (int r = 0; r < 16; ++r) p1[r] = __builtin_amdgcn_exp2f(p1[r]);
;   float ps = 0;
; #pragma unroll
;   for (int r = 0; r < 16; ++r) ps += p0[r];
; #pragma unroll
;   for (int r = 0; r < 16; ++r) ps += p1[r];
;   { auto rr = __builtin_amdgcn_permlane32_swap(__float_as_uint(ps), __float_as_uint(ps), false, false);
;     ps = __uint_as_float(rr[0]) + __uint_as_float(rr[1]); }
;   l_reg = l_reg * alpha + ps;
;     ...
;   PK4(p0, 0, pa0); PK4(p0, 8, pa1); PK4(p1, 0, pa2); PK4(p1, 8, pa3);
;     ...
; }
; template <int DQK, int KW, int QSP> __device__ __forceinline__ void qkt(f32x16& p0, f32x16& p1, const char* Ks, const int (&kb)[4], const bf16x8* qr, const char* qsp, const f32x16& cinit) {
;   p0 = cinit; p1 = cinit;
;   constexpr int N = DQK / 16;
;     ...
;   bf16x8 f0[2], f1[2];
;   f0[0] = KRD(0, 1); f1[0] = KRD(0, 0);
; #pragma unroll
;   for (int d0 = 0; d0 < N; ++d0) {
;     if (d0 + 1 < N) { f0[(d0 + 1) & 1] = KRD(d0 + 1, 1); f1[(d0 + 1) & 1] = KRD(d0 + 1, 0); }
;     __builtin_amdgcn_sched_barrier(0x406);
;     bf16x8 qf;
;     if constexpr (QSP > 0) { if (d0 >= N - QSP) qf = *reinterpret_cast<const bf16x8*>(qsp + (d0 - (N - QSP)) * 1024); else qf = qr[d0]; } else qf = qr[d0];
;     p0 = __builtin_amdgcn_mfma_f32_32x32x16_bf16(f0[d0 & 1], qf, p0, 0, 0, 0);
;     p1 = __builtin_amdgcn_mfma_f32_32x32x16_bf16(f1[d0 & 1], qf, p1, 0, 0, 0);
;     __builtin_amdgcn_sched_barrier(0x406); }
.LBB0_286:
	s_lshl_b32 s8, s30, 14
	s_add_i32 s6, s8, 0
	v_add_u32_e32 v208, s6, v163
	v_add_u32_e32 v209, s6, v158
	ds_read_b128 v[70:73], v209 offset:49152
	ds_read_b128 v[66:69], v209 offset:57344
	ds_read_b128 v[168:171], v208 offset:49152
	ds_read_b128 v[196:199], v208 offset:57344
	v_add_u32_e32 v212, s6, v164
	v_add_u32_e32 v213, s6, v165
	s_waitcnt lgkmcnt(3)
	v_mfma_f32_32x32x16_bf16 v[82:97], v[70:73], v[102:105], 0
	v_exp_f32_e32 v144, v144
	v_exp_f32_e32 v145, v145
	v_exp_f32_e32 v142, v142
	v_exp_f32_e32 v143, v143
	v_exp_f32_e32 v140, v140
	v_exp_f32_e32 v141, v141
	s_waitcnt lgkmcnt(2)
	v_mfma_f32_32x32x16_bf16 v[66:81], v[66:69], v[102:105], 0
	ds_read_b128 v[200:203], v212 offset:49152
	ds_read_b128 v[204:207], v212 offset:57344
	s_waitcnt lgkmcnt(3)
	v_mfma_f32_32x32x16_bf16 v[82:97], v[168:171], v[110:113], v[82:97]
	s_waitcnt lgkmcnt(2)
	v_mfma_f32_32x32x16_bf16 v[66:81], v[196:199], v[110:113], v[66:81]
	ds_read_b128 v[168:171], v213 offset:49152
	ds_read_b128 v[196:199], v213 offset:57344
	s_waitcnt lgkmcnt(3)
	v_mfma_f32_32x32x16_bf16 v[82:97], v[200:203], v[106:109], v[82:97]
	s_waitcnt lgkmcnt(2)
	v_mfma_f32_32x32x16_bf16 v[66:81], v[204:207], v[106:109], v[66:81]
	ds_read_b128 v[200:203], v209 offset:49280
	ds_read_b128 v[204:207], v209 offset:57472
	s_waitcnt lgkmcnt(3)
	v_mfma_f32_32x32x16_bf16 v[82:97], v[168:171], v[98:101], v[82:97]
	s_waitcnt lgkmcnt(2)
	v_mfma_f32_32x32x16_bf16 v[66:81], v[196:199], v[98:101], v[66:81]
	ds_read_b128 v[168:171], v208 offset:49280
	ds_read_b128 v[196:199], v208 offset:57472
	s_waitcnt lgkmcnt(3)
	v_mfma_f32_32x32x16_bf16 v[82:97], v[200:203], v[220:223], v[82:97]
	s_waitcnt lgkmcnt(2)
	v_mfma_f32_32x32x16_bf16 v[66:81], v[204:207], v[220:223], v[66:81]
	ds_read_b128 v[200:203], v212 offset:49280
	ds_read_b128 v[204:207], v212 offset:57472
	s_waitcnt lgkmcnt(3)
	v_mfma_f32_32x32x16_bf16 v[82:97], v[168:171], v[224:227], v[82:97]
	s_waitcnt lgkmcnt(2)
	v_mfma_f32_32x32x16_bf16 v[66:81], v[196:199], v[224:227], v[66:81]
	ds_read_b128 v[168:171], v213 offset:49280
	ds_read_b128 v[196:199], v213 offset:57472
	s_waitcnt lgkmcnt(3)
	v_mfma_f32_32x32x16_bf16 v[82:97], v[200:203], v[228:231], v[82:97]
	s_waitcnt lgkmcnt(2)
	v_mfma_f32_32x32x16_bf16 v[66:81], v[204:207], v[228:231], v[66:81]
	s_waitcnt lgkmcnt(0)
	v_mfma_f32_32x32x16_bf16 v[82:97], v[168:171], v[232:235], v[82:97]
	v_exp_f32_e32 v170, v138
	v_exp_f32_e32 v171, v139
	v_mfma_f32_32x32x16_bf16 v[66:81], v[196:199], v[232:235], v[66:81]
	v_exp_f32_e32 v202, v130
	v_add_f32_e32 v130, 0, v193
	v_add_f32_e32 v130, v195, v130
	v_add_f32_e32 v130, v183, v130
	v_add_f32_e32 v130, v194, v130
	v_add_f32_e32 v130, v181, v130
	v_add_f32_e32 v130, v192, v130
	v_add_f32_e32 v130, v180, v130
	v_add_f32_e32 v130, v182, v130
	v_add_f32_e32 v130, v177, v130
	v_add_f32_e32 v130, v179, v130
	v_add_f32_e32 v130, v175, v130
	v_add_f32_e32 v130, v178, v130
	v_add_f32_e32 v130, v173, v130
	v_add_f32_e32 v130, v176, v130
	v_add_f32_e32 v130, v172, v130
	v_add_f32_e32 v130, v174, v130
	v_add_f32_e32 v130, v144, v130
	v_add_f32_e32 v130, v145, v130
	v_add_f32_e32 v130, v142, v130
	v_add_f32_e32 v130, v143, v130
	v_exp_f32_e32 v196, v136
	v_add_f32_e32 v130, v140, v130
	v_exp_f32_e32 v197, v137
	v_add_f32_e32 v130, v141, v130
	v_exp_f32_e32 v198, v134
	v_add_f32_e32 v130, v170, v130
	v_exp_f32_e32 v199, v135
	v_add_f32_e32 v130, v171, v130
	v_exp_f32_e32 v200, v132
	v_add_f32_e32 v130, v196, v130
	v_exp_f32_e32 v201, v133
	v_add_f32_e32 v130, v197, v130
	v_add_f32_e32 v130, v198, v130
	v_exp_f32_e32 v203, v131
	v_add_f32_e32 v130, v199, v130
	v_add_f32_e32 v130, v200, v130
	v_add_f32_e32 v130, v201, v130
	v_add_f32_e32 v130, v202, v130
	v_add_f32_e32 v168, v203, v130
	v_mov_b32_e32 v169, v168
	v_cvt_pk_bf16_f32 v130, v193, v195
	v_cvt_pk_bf16_f32 v131, v183, v194
	v_cvt_pk_bf16_f32 v132, v181, v192
	s_nop 1
	v_permlane32_swap_b32_e32 v168, v169
	v_cvt_pk_bf16_f32 v133, v180, v182
	v_permlane32_swap_b32_e32 v130, v132
	v_cvt_pk_bf16_f32 v134, v177, v179
	v_cvt_pk_bf16_f32 v135, v175, v178
	v_cvt_pk_bf16_f32 v136, v173, v176
	v_cvt_pk_bf16_f32 v137, v172, v174
	v_cvt_pk_bf16_f32 v138, v144, v145
	v_cvt_pk_bf16_f32 v139, v142, v143
	v_cvt_pk_bf16_f32 v140, v140, v141
	v_cvt_pk_bf16_f32 v141, v170, v171
	v_cvt_pk_bf16_f32 v142, v196, v197
	v_cvt_pk_bf16_f32 v143, v198, v199
	v_cvt_pk_bf16_f32 v144, v200, v201
	v_cvt_pk_bf16_f32 v145, v202, v203
	v_permlane32_swap_b32_e32 v131, v133
	v_permlane32_swap_b32_e32 v134, v136
	v_permlane32_swap_b32_e32 v135, v137
	v_permlane32_swap_b32_e32 v138, v140
	v_permlane32_swap_b32_e32 v139, v141
	v_permlane32_swap_b32_e32 v142, v144
	v_permlane32_swap_b32_e32 v143, v145
	s_lshl_b32 s28, s27, 14
	s_add_i32 s9, s28, 0
	v_add_u32_e32 v170, s9, v159
	s_waitcnt vmcnt(0)
	s_waitcnt vmcnt(3)
	ds_write_b128 v170, v[114:117]
	v_add_u32_e32 v114, s9, v160
	s_waitcnt vmcnt(1)
	ds_write_b128 v114, v[118:121]
	v_add_u32_e32 v114, s9, v161
	s_mov_b32 s6, 0xfffe8000
	s_waitcnt vmcnt(1)
	ds_write_b128 v114, v[122:125] offset:49152
	s_waitcnt vmcnt(0)
	ds_write_b128 v114, v[126:129] offset:57344
	v_add_co_u32_e32 v114, vcc, s6, v148
	s_mov_b32 s6, 0xfb7e8000
	s_nop 0
	v_addc_co_u32_e32 v115, vcc, -1, v149, vcc
	v_add_co_u32_e32 v118, vcc, s3, v148
	s_nop 1
	v_addc_co_u32_e32 v119, vcc, -1, v149, vcc
	v_add_co_u32_e32 v122, vcc, s6, v148
	s_mov_b32 s6, 0xfb7f0000
	s_nop 0
	v_addc_co_u32_e32 v123, vcc, -1, v149, vcc
	v_add_co_u32_e32 v126, vcc, s6, v148
	global_load_dwordx4 v[114:117], v[114:115], off
	s_nop 0
	global_load_dwordx4 v[118:121], v[118:119], off
	v_addc_co_u32_e32 v127, vcc, -1, v149, vcc
	global_load_dwordx4 v[122:125], v[122:123], off
	s_nop 0
	global_load_dwordx4 v[126:129], v[126:127], off
	v_lshl_add_u32 v182, s48, 14, v154
	ds_read_b64_tr_b16 v[170:171], v182 offset:0
	ds_read_b64_tr_b16 v[172:173], v182 offset:0x800
	ds_read_b64_tr_b16 v[174:175], v182 offset:0x1000
	ds_read_b64_tr_b16 v[176:177], v182 offset:0x1800
	ds_read_b64_tr_b16 v[178:179], v182 offset:0x2000
	ds_read_b64_tr_b16 v[180:181], v182 offset:0x2800
	ds_read_b64_tr_b16 v[192:193], v182 offset:0x3000
	ds_read_b64_tr_b16 v[194:195], v182 offset:0x3800
	s_waitcnt lgkmcnt(6)
; #define SBAR() __builtin_amdgcn_sched_barrier(0)
; template <int DQK> __device__ __forceinline__ void partialSM(f32x16& p0, f32x16& p1, float& m_reg, float& mn, float& alpha) {
;   constexpr float SCALE = Sc<DQK>::SCALE; constexpr float C = SCALE * 1.4426950408889634f;
;   float pmax = p0[0];
; #pragma unroll
;   for (int r = 1; r < 16; ++r) pmax = fmaxf(pmax, p0[r]);
; #pragma unroll
;   for (int r = 0; r < 16; ++r) pmax = fmaxf(pmax, p1[r]);
;   { auto rr = __builtin_amdgcn_permlane32_swap(__float_as_uint(pmax), __float_as_uint(pmax), false, false);
;     pmax = fmaxf(__uint_as_float(rr[0]), __uint_as_float(rr[1])); }
;   if (__builtin_expect(__all(pmax - m_reg <= THR / SCALE), 1)) { mn = m_reg; alpha = 1.f; }
;   else { mn = fmaxf(m_reg, pmax); alpha = __builtin_amdgcn_exp2f((m_reg - mn) * C); m_reg = mn; }
; template <int D0> __device__ __forceinline__ void pv_one(f32x16& od, int vb, bf16x8 pa0, bf16x8 pa1, bf16x8 pa2, bf16x8 pa3) {
;   const s16x4 l0 = tr_read<v_rd_off(D0, 0, 0)>(vb), h0 = tr_read<v_rd_off(D0, 0, 1)>(vb), l1 = tr_read<v_rd_off(D0, 1, 0)>(vb), h1 = tr_read<v_rd_off(D0, 1, 1)>(vb);
;   const s16x4 l2 = tr_read<v_rd_off(D0, 2, 0)>(vb), h2 = tr_read<v_rd_off(D0, 2, 1)>(vb), l3 = tr_read<v_rd_off(D0, 3, 0)>(vb), h3 = tr_read<v_rd_off(D0, 3, 1)>(vb);
;   asm volatile("s_waitcnt lgkmcnt(0)" ::: "memory"); SBAR();
;     ...
;   od = __builtin_amdgcn_mfma_f32_32x32x16_bf16(pa0, PK(l0, h0), od, 0, 0, 0);
;   od = __builtin_amdgcn_mfma_f32_32x32x16_bf16(pa1, PK(l1, h1), od, 0, 0, 0);
;   od = __builtin_amdgcn_mfma_f32_32x32x16_bf16(pa2, PK(l2, h2), od, 0, 0, 0);
;   od = __builtin_amdgcn_mfma_f32_32x32x16_bf16(pa3, PK(l3, h3), od, 0, 0, 0);
;     ...
; }
	s_nop 0
	v_mfma_f32_32x32x16_bf16 v[2:17], v[130:133], v[170:173], v[2:17]
	ds_read_b64_tr_b16 v[170:171], v182 offset:0x200
	ds_read_b64_tr_b16 v[172:173], v182 offset:0xa00
	s_waitcnt lgkmcnt(6)
	v_mfma_f32_32x32x16_bf16 v[2:17], v[134:137], v[174:177], v[2:17]
	ds_read_b64_tr_b16 v[174:175], v182 offset:0x1200
	ds_read_b64_tr_b16 v[176:177], v182 offset:0x1a00
	s_waitcnt lgkmcnt(6)
	v_mfma_f32_32x32x16_bf16 v[2:17], v[138:141], v[178:181], v[2:17]
	ds_read_b64_tr_b16 v[178:179], v182 offset:0x2200
	ds_read_b64_tr_b16 v[180:181], v182 offset:0x2a00
	s_waitcnt lgkmcnt(6)
	v_mfma_f32_32x32x16_bf16 v[2:17], v[142:145], v[192:195], v[2:17]
	ds_read_b64_tr_b16 v[192:193], v182 offset:0x3200
	ds_read_b64_tr_b16 v[194:195], v182 offset:0x3a00
	s_waitcnt lgkmcnt(6)
	v_mfma_f32_32x32x16_bf16 v[50:65], v[130:133], v[170:173], v[50:65]
	ds_read_b64_tr_b16 v[170:171], v182 offset:0x400
	ds_read_b64_tr_b16 v[172:173], v182 offset:0xc00
	s_waitcnt lgkmcnt(6)
	v_mfma_f32_32x32x16_bf16 v[50:65], v[134:137], v[174:177], v[50:65]
	ds_read_b64_tr_b16 v[174:175], v182 offset:0x1400
	ds_read_b64_tr_b16 v[176:177], v182 offset:0x1c00
	s_waitcnt lgkmcnt(6)
	v_mfma_f32_32x32x16_bf16 v[50:65], v[138:141], v[178:181], v[50:65]
	ds_read_b64_tr_b16 v[178:179], v182 offset:0x2400
	ds_read_b64_tr_b16 v[180:181], v182 offset:0x2c00
	s_waitcnt lgkmcnt(6)
	v_mfma_f32_32x32x16_bf16 v[50:65], v[142:145], v[192:195], v[50:65]
	ds_read_b64_tr_b16 v[192:193], v182 offset:0x3400
	ds_read_b64_tr_b16 v[194:195], v182 offset:0x3c00
	s_waitcnt lgkmcnt(6)
	v_mfma_f32_32x32x16_bf16 v[34:49], v[130:133], v[170:173], v[34:49]
	ds_read_b64_tr_b16 v[170:171], v182 offset:0x600
	ds_read_b64_tr_b16 v[172:173], v182 offset:0xe00
	s_waitcnt lgkmcnt(6)
	v_mfma_f32_32x32x16_bf16 v[34:49], v[134:137], v[174:177], v[34:49]
	ds_read_b64_tr_b16 v[174:175], v182 offset:0x1600
	ds_read_b64_tr_b16 v[176:177], v182 offset:0x1e00
	s_waitcnt lgkmcnt(6)
	v_mfma_f32_32x32x16_bf16 v[34:49], v[138:141], v[178:181], v[34:49]
	ds_read_b64_tr_b16 v[178:179], v182 offset:0x2600
	ds_read_b64_tr_b16 v[180:181], v182 offset:0x2e00
	s_waitcnt lgkmcnt(6)
	v_mfma_f32_32x32x16_bf16 v[34:49], v[142:145], v[192:195], v[34:49]
	ds_read_b64_tr_b16 v[192:193], v182 offset:0x3600
	ds_read_b64_tr_b16 v[194:195], v182 offset:0x3e00
	s_waitcnt lgkmcnt(6)
	v_mfma_f32_32x32x16_bf16 v[18:33], v[130:133], v[170:173], v[18:33]
	v_max_f32_e32 v130, v83, v83
	v_max_f32_e32 v131, v82, v82
	v_max_f32_e32 v130, v131, v130
	v_max3_f32 v130, v130, v84, v85
	v_max3_f32 v130, v130, v86, v87
	v_max3_f32 v130, v130, v88, v89
	v_max3_f32 v130, v130, v90, v91
	v_max3_f32 v130, v130, v92, v93
	v_max3_f32 v130, v130, v94, v95
	s_waitcnt lgkmcnt(4)
	v_mfma_f32_32x32x16_bf16 v[18:33], v[134:137], v[174:177], v[18:33]
	v_max3_f32 v130, v130, v96, v97
	v_max3_f32 v130, v130, v66, v67
	v_max3_f32 v130, v130, v68, v69
	v_max3_f32 v130, v130, v70, v71
	v_max3_f32 v130, v130, v72, v73
	v_max3_f32 v130, v130, v74, v75
	v_max3_f32 v130, v130, v76, v77
	v_max3_f32 v130, v130, v78, v79
	s_waitcnt lgkmcnt(2)
	v_mfma_f32_32x32x16_bf16 v[18:33], v[138:141], v[178:181], v[18:33]
	v_max3_f32 v130, v130, v80, v81
	v_mov_b32_e32 v131, v130
	s_nop 1
	v_permlane32_swap_b32_e32 v130, v131
	v_max_f32_e32 v131, v131, v131
	v_max_f32_e32 v130, v130, v130
	v_max_f32_e32 v130, v130, v131
	v_sub_f32_e32 v131, v130, v167
	v_cmp_ge_f32_e32 vcc, s33, v131
	v_max_f32_e32 v131, v167, v167
	v_max_f32_e32 v130, v131, v130
	s_waitcnt lgkmcnt(0)
	v_mfma_f32_32x32x16_bf16 v[18:33], v[142:145], v[192:195], v[18:33]
	v_sub_f32_e32 v131, v167, v130
	v_mul_f32_e32 v131, 0x3e0293ee, v131
	v_exp_f32_e32 v131, v131
	s_cmp_eq_u64 vcc, exec
	s_cselect_b64 s[40:41], -1, 0
	s_waitcnt lgkmcnt(0)
	s_barrier
	v_cndmask_b32_e64 v171, v131, 1.0, s[40:41]
	v_cmp_gt_f32_e32 vcc, 1.0, v171
	s_cbranch_vccz .LBB0_290
	s_and_saveexec_b64 s[6:7], s[38:39]
	ds_write_b32 v155, v171 offset:128
	s_or_b64 exec, exec, s[6:7]
	s_waitcnt lgkmcnt(0)
	v_add_u32_e32 v131, v153, v146
	ds_read_b128 v[132:135], v131 offset:224
	ds_read_b128 v[136:139], v131 offset:192
	ds_read_b128 v[140:143], v131 offset:160
	ds_read_b128 v[172:175], v131 offset:128
	s_waitcnt lgkmcnt(3)
	v_pk_mul_f32 v[14:15], v[14:15], v[132:133]
	s_waitcnt lgkmcnt(2)
	v_pk_mul_f32 v[10:11], v[10:11], v[136:137]
	s_waitcnt lgkmcnt(1)
	v_pk_mul_f32 v[6:7], v[6:7], v[140:141]
	v_pk_mul_f32 v[16:17], v[16:17], v[134:135]
	v_pk_mul_f32 v[12:13], v[12:13], v[138:139]
	v_pk_mul_f32 v[8:9], v[8:9], v[142:143]
	s_waitcnt lgkmcnt(0)
	v_pk_mul_f32 v[4:5], v[4:5], v[174:175]
	v_pk_mul_f32 v[2:3], v[2:3], v[172:173]
	v_pk_mul_f32 v[62:63], v[62:63], v[132:133]
	v_pk_mul_f32 v[58:59], v[58:59], v[136:137]
	v_pk_mul_f32 v[54:55], v[54:55], v[140:141]
	v_pk_mul_f32 v[64:65], v[64:65], v[134:135]
	v_pk_mul_f32 v[60:61], v[60:61], v[138:139]
	v_pk_mul_f32 v[56:57], v[56:57], v[142:143]
	v_pk_mul_f32 v[52:53], v[52:53], v[174:175]
	v_pk_mul_f32 v[50:51], v[50:51], v[172:173]
	v_pk_mul_f32 v[46:47], v[46:47], v[132:133]
	v_pk_mul_f32 v[42:43], v[42:43], v[136:137]
	v_pk_mul_f32 v[38:39], v[38:39], v[140:141]
	v_pk_mul_f32 v[48:49], v[48:49], v[134:135]
	v_pk_mul_f32 v[44:45], v[44:45], v[138:139]
	v_pk_mul_f32 v[40:41], v[40:41], v[142:143]
	v_pk_mul_f32 v[36:37], v[36:37], v[174:175]
	v_pk_mul_f32 v[34:35], v[34:35], v[172:173]
	v_pk_mul_f32 v[30:31], v[30:31], v[132:133]
	v_pk_mul_f32 v[26:27], v[26:27], v[136:137]
	v_pk_mul_f32 v[22:23], v[22:23], v[140:141]
	v_pk_mul_f32 v[32:33], v[32:33], v[134:135]
	v_pk_mul_f32 v[28:29], v[28:29], v[138:139]
	v_pk_mul_f32 v[24:25], v[24:25], v[142:143]
	v_pk_mul_f32 v[20:21], v[20:21], v[174:175]
	v_pk_mul_f32 v[18:19], v[18:19], v[172:173]
; template <int DQK> __device__ __forceinline__ void partialSM(f32x16& p0, f32x16& p1, float& m_reg, float& mn, float& alpha) {
;     ...
;   float mnC = -mn * C;
; #pragma unroll
;   for (int r = 0; r < 16; ++r) p0[r] = fmaf(p0[r], C, mnC);
; #pragma unroll
;   for (int r = 0; r < 16; ++r) p1[r] = fmaf(p1[r], C, mnC);
; #pragma unroll
;   for (int r = 0; r < 16; ++r) p0[r] = __builtin_amdgcn_exp2f(p0[r]);
; __device__ __forceinline__ void finishSM(f32x16& p0, f32x16& p1, float alpha, float& l_reg, bf16x8& pa0, bf16x8& pa1, bf16x8& pa2, bf16x8& pa3) {
; #pragma unroll
;   for (int r = 0; r < 16; ++r) p1[r] = __builtin_amdgcn_exp2f(p1[r]);
;   float ps = 0;
; #pragma unroll
;   for (int r = 0; r < 16; ++r) ps += p0[r];
; #pragma unroll
;   for (int r = 0; r < 16; ++r) ps += p1[r];
;   { auto rr = __builtin_amdgcn_permlane32_swap(__float_as_uint(ps), __float_as_uint(ps), false, false);
;     ps = __uint_as_float(rr[0]) + __uint_as_float(rr[1]); }
;   l_reg = l_reg * alpha + ps;
;     ...
;   PK4(p0, 0, pa0); PK4(p0, 8, pa1); PK4(p1, 0, pa2); PK4(p1, 8, pa3);
;     ...
; }
; template <int DQK, int KW, int QSP> __device__ __forceinline__ void qkt(f32x16& p0, f32x16& p1, const char* Ks, const int (&kb)[4], const bf16x8* qr, const char* qsp, const f32x16& cinit) {
;   p0 = cinit; p1 = cinit;
;   constexpr int N = DQK / 16;
;     ...
;   bf16x8 f0[2], f1[2];
;   f0[0] = KRD(0, 1); f1[0] = KRD(0, 0);
; #pragma unroll
;   for (int d0 = 0; d0 < N; ++d0) {
;     if (d0 + 1 < N) { f0[(d0 + 1) & 1] = KRD(d0 + 1, 1); f1[(d0 + 1) & 1] = KRD(d0 + 1, 0); }
;     __builtin_amdgcn_sched_barrier(0x406);
;     bf16x8 qf;
;     if constexpr (QSP > 0) { if (d0 >= N - QSP) qf = *reinterpret_cast<const bf16x8*>(qsp + (d0 - (N - QSP)) * 1024); else qf = qr[d0]; } else qf = qr[d0];
;     p0 = __builtin_amdgcn_mfma_f32_32x32x16_bf16(f0[d0 & 1], qf, p0, 0, 0, 0);
;     p1 = __builtin_amdgcn_mfma_f32_32x32x16_bf16(f1[d0 & 1], qf, p1, 0, 0, 0);
;     __builtin_amdgcn_sched_barrier(0x406); }
.LBB0_290:
	v_cndmask_b32_e64 v167, v130, v167, s[40:41]
	s_add_i32 s6, s27, 1
	v_mul_f32_e32 v170, 0xbe0293ee, v167
	s_cmp_lg_u32 s27, 2
	v_fmamk_f32 v82, v82, 0x3e0293ee, v170
	v_fmamk_f32 v83, v83, 0x3e0293ee, v170
	v_fmamk_f32 v84, v84, 0x3e0293ee, v170
	v_fmamk_f32 v85, v85, 0x3e0293ee, v170
	v_fmamk_f32 v86, v86, 0x3e0293ee, v170
	v_fmamk_f32 v87, v87, 0x3e0293ee, v170
	v_fmamk_f32 v88, v88, 0x3e0293ee, v170
	v_fmamk_f32 v89, v89, 0x3e0293ee, v170
	v_fmamk_f32 v90, v90, 0x3e0293ee, v170
	v_fmamk_f32 v91, v91, 0x3e0293ee, v170
	v_fmamk_f32 v92, v92, 0x3e0293ee, v170
	v_fmamk_f32 v93, v93, 0x3e0293ee, v170
	v_fmamk_f32 v94, v94, 0x3e0293ee, v170
	v_fmamk_f32 v95, v95, 0x3e0293ee, v170
	v_fmamk_f32 v96, v96, 0x3e0293ee, v170
	v_fmamk_f32 v97, v97, 0x3e0293ee, v170
	v_fmamk_f32 v196, v78, 0x3e0293ee, v170
	v_fmamk_f32 v197, v79, 0x3e0293ee, v170
	s_cselect_b32 s30, s6, 0
	v_fmamk_f32 v176, v66, 0x3e0293ee, v170
	v_fmamk_f32 v177, v67, 0x3e0293ee, v170
	v_fmamk_f32 v178, v68, 0x3e0293ee, v170
	v_fmamk_f32 v179, v69, 0x3e0293ee, v170
	v_fmamk_f32 v180, v70, 0x3e0293ee, v170
	v_fmamk_f32 v181, v71, 0x3e0293ee, v170
	v_fmamk_f32 v182, v72, 0x3e0293ee, v170
	v_fmamk_f32 v183, v73, 0x3e0293ee, v170
	v_fmamk_f32 v192, v74, 0x3e0293ee, v170
	v_fmamk_f32 v193, v75, 0x3e0293ee, v170
	v_fmamk_f32 v194, v76, 0x3e0293ee, v170
	v_fmamk_f32 v195, v77, 0x3e0293ee, v170
	v_fmamk_f32 v198, v80, 0x3e0293ee, v170
	v_fmac_f32_e32 v170, 0x3e0293ee, v81
	v_exp_f32_e32 v199, v82
	v_exp_f32_e32 v200, v83
	v_exp_f32_e32 v201, v84
	v_exp_f32_e32 v202, v85
	v_exp_f32_e32 v203, v86
	v_exp_f32_e32 v204, v87
	v_exp_f32_e32 v205, v88
	v_exp_f32_e32 v206, v89
	v_exp_f32_e32 v207, v90
	v_exp_f32_e32 v208, v91
	v_exp_f32_e32 v209, v92
	v_exp_f32_e32 v210, v93
	v_exp_f32_e32 v211, v94
	v_exp_f32_e32 v212, v95
	v_exp_f32_e32 v213, v96
	v_exp_f32_e32 v214, v97
	v_add_u32_e32 v172, s9, v163
	v_add_u32_e32 v173, s9, v158
	ds_read_b128 v[70:73], v173 offset:49152
	ds_read_b128 v[66:69], v173 offset:57344
	ds_read_b128 v[130:133], v172 offset:49152
	ds_read_b128 v[134:137], v172 offset:57344
	v_add_u32_e32 v215, s9, v164
	v_add_u32_e32 v216, s9, v165
	s_waitcnt lgkmcnt(3)
	v_mfma_f32_32x32x16_bf16 v[82:97], v[70:73], v[102:105], 0
	v_exp_f32_e32 v170, v170
	s_waitcnt lgkmcnt(2)
	v_mfma_f32_32x32x16_bf16 v[66:81], v[66:69], v[102:105], 0
	ds_read_b128 v[138:141], v215 offset:49152
	ds_read_b128 v[142:145], v215 offset:57344
	s_waitcnt lgkmcnt(3)
	v_mfma_f32_32x32x16_bf16 v[82:97], v[130:133], v[110:113], v[82:97]
	s_waitcnt lgkmcnt(2)
	v_mfma_f32_32x32x16_bf16 v[66:81], v[134:137], v[110:113], v[66:81]
	ds_read_b128 v[130:133], v216 offset:49152
	ds_read_b128 v[134:137], v216 offset:57344
	s_waitcnt lgkmcnt(3)
	v_mfma_f32_32x32x16_bf16 v[82:97], v[138:141], v[106:109], v[82:97]
	s_waitcnt lgkmcnt(2)
	v_mfma_f32_32x32x16_bf16 v[66:81], v[142:145], v[106:109], v[66:81]
	ds_read_b128 v[138:141], v173 offset:49280
	ds_read_b128 v[142:145], v173 offset:57472
	s_waitcnt lgkmcnt(3)
	v_mfma_f32_32x32x16_bf16 v[82:97], v[130:133], v[98:101], v[82:97]
	s_waitcnt lgkmcnt(2)
	v_mfma_f32_32x32x16_bf16 v[66:81], v[134:137], v[98:101], v[66:81]
	ds_read_b128 v[130:133], v172 offset:49280
	ds_read_b128 v[134:137], v172 offset:57472
	s_waitcnt lgkmcnt(3)
	v_mfma_f32_32x32x16_bf16 v[82:97], v[138:141], v[220:223], v[82:97]
	s_waitcnt lgkmcnt(2)
	v_mfma_f32_32x32x16_bf16 v[66:81], v[142:145], v[220:223], v[66:81]
	ds_read_b128 v[138:141], v215 offset:49280
	ds_read_b128 v[142:145], v215 offset:57472
	s_waitcnt lgkmcnt(3)
	v_mfma_f32_32x32x16_bf16 v[82:97], v[130:133], v[224:227], v[82:97]
	s_waitcnt lgkmcnt(2)
	v_mfma_f32_32x32x16_bf16 v[66:81], v[134:137], v[224:227], v[66:81]
	ds_read_b128 v[130:133], v216 offset:49280
	ds_read_b128 v[134:137], v216 offset:57472
	s_waitcnt lgkmcnt(3)
	v_mfma_f32_32x32x16_bf16 v[82:97], v[138:141], v[228:231], v[82:97]
	s_waitcnt lgkmcnt(2)
	v_mfma_f32_32x32x16_bf16 v[66:81], v[142:145], v[228:231], v[66:81]
	v_exp_f32_e32 v142, v180
	v_exp_f32_e32 v143, v181
	v_exp_f32_e32 v144, v182
	v_exp_f32_e32 v145, v183
	v_exp_f32_e32 v172, v192
	v_exp_f32_e32 v173, v193
	s_waitcnt lgkmcnt(0)
	v_mfma_f32_32x32x16_bf16 v[82:97], v[130:133], v[232:235], v[82:97]
	v_add_f32_e32 v130, 0, v199
	v_add_f32_e32 v130, v200, v130
	v_add_f32_e32 v130, v201, v130
	v_add_f32_e32 v130, v202, v130
	v_add_f32_e32 v130, v203, v130
	v_add_f32_e32 v130, v204, v130
	v_add_f32_e32 v130, v205, v130
	v_add_f32_e32 v130, v206, v130
	v_add_f32_e32 v130, v207, v130
	v_add_f32_e32 v130, v208, v130
	v_add_f32_e32 v130, v209, v130
	v_add_f32_e32 v130, v210, v130
	v_mfma_f32_32x32x16_bf16 v[66:81], v[134:137], v[232:235], v[66:81]
	v_exp_f32_e32 v138, v176
	v_add_f32_e32 v130, v211, v130
	v_exp_f32_e32 v139, v177
	v_add_f32_e32 v130, v212, v130
	v_exp_f32_e32 v140, v178
	v_add_f32_e32 v130, v213, v130
	v_exp_f32_e32 v141, v179
	v_add_f32_e32 v130, v214, v130
	v_add_f32_e32 v130, v138, v130
	v_add_f32_e32 v130, v139, v130
	v_add_f32_e32 v130, v140, v130
	v_add_f32_e32 v130, v141, v130
	v_add_f32_e32 v130, v142, v130
	v_add_f32_e32 v130, v143, v130
	v_exp_f32_e32 v174, v194
	v_add_f32_e32 v130, v144, v130
	v_exp_f32_e32 v175, v195
	v_add_f32_e32 v130, v145, v130
	v_exp_f32_e32 v176, v196
	v_add_f32_e32 v130, v172, v130
	v_exp_f32_e32 v177, v197
	v_add_f32_e32 v130, v173, v130
	v_exp_f32_e32 v178, v198
	v_add_f32_e32 v130, v174, v130
	v_add_f32_e32 v130, v175, v130
	v_add_f32_e32 v130, v176, v130
	v_add_f32_e32 v130, v177, v130
	v_add_f32_e32 v130, v178, v130
	v_add_f32_e32 v196, v170, v130
	v_mov_b32_e32 v197, v196
	v_cvt_pk_bf16_f32 v130, v199, v200
	v_cvt_pk_bf16_f32 v131, v201, v202
	v_cvt_pk_bf16_f32 v132, v203, v204
	v_cvt_pk_bf16_f32 v133, v205, v206
	v_cvt_pk_bf16_f32 v134, v207, v208
	v_cvt_pk_bf16_f32 v135, v209, v210
	v_cvt_pk_bf16_f32 v136, v211, v212
	v_cvt_pk_bf16_f32 v137, v213, v214
	v_cvt_pk_bf16_f32 v138, v138, v139
	v_cvt_pk_bf16_f32 v139, v140, v141
	v_cvt_pk_bf16_f32 v140, v142, v143
	v_cvt_pk_bf16_f32 v141, v144, v145
	v_cvt_pk_bf16_f32 v142, v172, v173
	v_cvt_pk_bf16_f32 v143, v174, v175
	v_cvt_pk_bf16_f32 v144, v176, v177
	v_cvt_pk_bf16_f32 v145, v178, v170
	s_nop 1
	v_permlane32_swap_b32_e32 v196, v197
	v_permlane32_swap_b32_e32 v130, v132
	v_permlane32_swap_b32_e32 v131, v133
	v_permlane32_swap_b32_e32 v134, v136
	v_permlane32_swap_b32_e32 v135, v137
	v_permlane32_swap_b32_e32 v138, v140
	v_permlane32_swap_b32_e32 v139, v141
	v_permlane32_swap_b32_e32 v142, v144
	v_permlane32_swap_b32_e32 v143, v145
	s_lshl_b32 s29, s30, 14
	s_add_i32 s31, s29, 0
	s_waitcnt vmcnt(0)
	v_add_u32_e32 v170, s31, v159
	s_cmp_ge_u32 s25, s26
	s_waitcnt vmcnt(3)
	ds_write_b128 v170, v[114:117]
	v_add_u32_e32 v170, s31, v160
	s_cselect_b64 s[6:7], -1, 0
	s_waitcnt vmcnt(2)
	ds_write_b128 v170, v[118:121]
	v_add_u32_e32 v170, s29, v162
	s_and_b64 vcc, exec, s[6:7]
	s_waitcnt vmcnt(1)
	ds_write_b128 v170, v[122:125] offset:49152
	s_waitcnt vmcnt(0)
	ds_write_b128 v170, v[126:129] offset:57344
	s_cbranch_vccnz .LBB0_292
	v_add_co_u32_e32 v114, vcc, 0xffff8000, v148
	s_nop 1
	v_addc_co_u32_e32 v115, vcc, -1, v149, vcc
	v_add_co_u32_e32 v118, vcc, 0xfb7f8000, v148
	s_nop 1
	v_addc_co_u32_e32 v119, vcc, -1, v149, vcc
	v_add_co_u32_e32 v126, vcc, 0xfb800000, v148
	global_load_dwordx4 v[114:117], v[114:115], off
	s_nop 0
	global_load_dwordx4 v[122:125], v[118:119], off
	v_addc_co_u32_e32 v127, vcc, -1, v149, vcc
	global_load_dwordx4 v[118:121], v[148:149], off
	s_nop 0
	global_load_dwordx4 v[126:129], v[126:127], off
